# GEMM (G1/G2/G3) epilogue stores as global instead of flat; mix-phase units no longer drain the previous unit's store acks before their first loads
# baseline (speedup 1.0000x reference)
; template <int NMAP, int VD, bool SWA> ...
;     ...
;     { const bf16_t* qr = Qp + (size_t)(16 * w + fr) * qpitch + fq * 8;
; #pragma unroll
;       for (int mp = 0; mp < NMAP; ++mp)
; #pragma unroll
;           for (int ks = 0; ks < 2; ++ks) qf[mp][ks] = *(const bf16x8*)(qr + mp * 64 + ks * 32); }
;     f32x4 oacc[NMAP][NET], negm[NMAP]; float mrun[NMAP], lsum[NMAP];
; #pragma unroll
;     for (int mp = 0; mp < NMAP; ++mp) { mrun[mp] = 0.f; lsum[mp] = 0.f; negm[mp] = (f32x4){0.f, 0.f, 0.f, 0.f};
; #pragma unroll
;         for (int et = 0; et < NET; ++et) oacc[mp][et] = (f32x4){0.f, 0.f, 0.f, 0.f}; }
;     const int ntiles = n0 + (t1hi - t1lo);
;     u32x4 kreg[NKC], vreg[NVC];
;     ...
;     ATT_LOAD(ATT_TILE(0));
;     ATT_STORE(0);
;     if (ntiles > 1) ATT_LOAD(ATT_TILE(1));
;     __syncthreads();
.LBB0_121:
	s_and_b32 s0, s22, 0xffffff00
	s_cmpk_eq_i32 s0, 0x200
	s_cselect_b64 s[0:1], -1, 0
	s_cmp_ge_i32 s22, s13
	s_cselect_b64 s[8:9], -1, 0
	s_or_b64 s[10:11], s[8:9], s[0:1]
	s_cmpk_gt_i32 s22, 0x2ff
	s_mov_b64 s[8:9], -1
	s_cselect_b64 s[0:1], -1, 0
	s_and_b64 vcc, exec, s[10:11]
	v_ashrrev_i32_e32 v178, 31, v176
	v_lshlrev_b32_e32 v175, 2, v177
	s_cbranch_vccnz .LBB0_139
	s_ashr_i32 s21, s20, 31
	s_lshl_b64 s[8:9], s[20:21], 10
	v_readlane_b32 s3, v252, 43
	s_add_u32 s3, s3, s8
	v_readlane_b32 s8, v252, 44
	s_addc_u32 s8, s8, s9
	s_lshl_b32 s25, s16, 7
	s_lshl_b32 s9, s16, 8
	s_waitcnt lgkmcnt(0)
	v_add_u32_e32 v22, 0x200, v176
	s_add_u32 s28, s3, s9
	v_lshrrev_b32_e32 v0, 28, v178
	v_ashrrev_i32_e32 v23, 31, v22
	s_addc_u32 s29, s8, 0
	s_lshl_b32 s14, s24, 2
	v_add_u32_e32 v0, v176, v0
	v_lshrrev_b32_e32 v23, 28, v23
	s_add_i32 s14, s14, s16
	v_ashrrev_i32_e32 v34, 4, v0
	v_add_u32_e32 v23, v22, v23
	s_mul_i32 s8, s14, 0x90000
	v_readlane_b32 s9, v252, 47
	v_and_b32_e32 v0, -16, v0
	v_ashrrev_i32_e32 v35, 31, v34
	v_ashrrev_i32_e32 v36, 4, v23
	v_and_b32_e32 v23, -16, v23
	s_mul_hi_i32 s3, s14, 0x90000
	s_add_u32 s10, s9, s8
	v_readlane_b32 s9, v252, 48
	v_sub_u32_e32 v0, v176, v0
	v_lshlrev_b64 v[58:59], 8, v[34:35]
	v_sub_u32_e32 v35, v22, v23
	s_addc_u32 s11, s9, s3
	v_readlane_b32 s9, v252, 49
	v_ashrrev_i32_e32 v161, 31, v160
	v_lshlrev_b32_e32 v20, 3, v0
	v_ashrrev_i32_e32 v37, 31, v36
	v_lshlrev_b32_e32 v24, 3, v35
	s_add_u32 s8, s9, s8
	v_readlane_b32 s9, v252, 50
	v_lshlrev_b64 v[2:3], 10, v[160:161]
	v_ashrrev_i32_e32 v21, 31, v20
	v_lshlrev_b64 v[94:95], 8, v[36:37]
	v_ashrrev_i32_e32 v25, 31, v24
	s_addc_u32 s9, s9, s3
	v_lshl_add_u64 v[2:3], s[28:29], 0, v[2:3]
	v_mov_b32_e32 v163, v1
	v_lshl_add_u64 v[18:19], s[10:11], 0, v[58:59]
	v_lshlrev_b64 v[60:61], 1, v[20:21]
	v_lshl_add_u64 v[22:23], s[10:11], 0, v[94:95]
	v_lshlrev_b64 v[96:97], 1, v[24:25]
	v_lshl_add_u64 v[2:3], v[2:3], 0, v[162:163]
	s_mov_b64 s[34:35], 0x4000
	v_lshl_add_u64 v[18:19], v[18:19], 0, v[60:61]
	v_lshl_add_u64 v[22:23], v[22:23], 0, v[96:97]
	v_lshl_add_u64 v[236:237], v[18:19], 0, s[34:35]
	v_lshl_add_u64 v[240:241], v[22:23], 0, s[34:35]
	v_lshl_add_u64 v[26:27], s[8:9], 0, v[58:59]
	global_load_dwordx4 v[14:17], v[2:3], off
	global_load_dwordx4 v[10:13], v[2:3], off offset:64
	global_load_dwordx4 v[6:9], v[2:3], off offset:128
	s_nop 0
	global_load_dwordx4 v[2:5], v[2:3], off offset:192
	v_lshl_add_u64 v[26:27], v[26:27], 0, v[60:61]
	v_lshl_add_u64 v[244:245], v[26:27], 0, s[34:35]
	global_load_dwordx4 v[18:21], v[18:19], off
	v_lshl_add_u64 v[30:31], s[8:9], 0, v[94:95]
	global_load_dwordx4 v[22:25], v[22:23], off
	v_lshl_add_u64 v[30:31], v[30:31], 0, v[96:97]
	v_lshl_add_u64 v[248:249], v[30:31], 0, s[34:35]
	global_load_dwordx4 v[26:29], v[26:27], off
	s_movk_i32 s15, 0x120
	global_load_dwordx4 v[30:33], v[30:31], off
	global_load_dwordx4 v[236:239], v[236:237], off
	global_load_dwordx4 v[240:243], v[240:241], off
	global_load_dwordx4 v[244:247], v[244:245], off
	global_load_dwordx4 v[248:251], v[248:249], off
	v_mul_lo_u32 v208, v34, s15
	v_lshlrev_b32_e32 v209, 4, v0
	v_mul_lo_u32 v210, v36, s15
	v_lshlrev_b32_e32 v211, 4, v35
	v_add3_u32 v34, 0, v208, v209
	v_add3_u32 v35, 0, v210, v211
	s_mov_b64 s[34:35], 0x4000
	v_lshlrev_b32_e32 v36, 2, v176
	v_and_b32_e32 v56, 12, v36
	v_mbcnt_hi_u32_b32 v36, -1, v190
	v_and_b32_e32 v38, 64, v36
	v_xor_b32_e32 v37, 16, v36
	v_add_u32_e32 v38, 64, v38
	v_cmp_lt_i32_e32 vcc, v37, v38
	v_mul_u32_u24_e32 v182, 0x120, v173
	v_add3_u32 v57, 0, v162, v182
	v_cndmask_b32_e32 v37, v36, v37, vcc
	v_lshlrev_b32_e32 v179, 2, v37
	v_xor_b32_e32 v37, 32, v36
	v_cmp_lt_i32_e32 vcc, v37, v38
	v_readlane_b32 s28, v254, 39
	v_readlane_b32 s29, v254, 40
	v_cndmask_b32_e32 v36, v36, v37, vcc
	v_lshlrev_b32_e32 v180, 2, v36
	v_lshlrev_b32_e32 v163, 2, v177
	v_bfe_u32 v0, v176, 2, 2
	s_mov_b32 s26, s28
	v_readlane_b32 s28, v254, 43
	v_or_b32_e32 v0, v163, v0
	v_readlane_b32 s29, v254, 44
	v_lshlrev_b32_e32 v107, 3, v177
	s_mov_b32 s3, 1
	v_mul_u32_u24_e32 v0, 0x120, v0
	s_waitcnt vmcnt(7)
	ds_write_b128 v34, v[18:21]
	s_waitcnt vmcnt(6)
	ds_write_b128 v35, v[22:25]
	s_waitcnt vmcnt(5)
	ds_write_b128 v34, v[26:29] offset:18432
	s_waitcnt vmcnt(4)
	ds_write_b128 v35, v[30:33] offset:18432
	s_mov_b64 s[34:35], 0x8000
	s_waitcnt lgkmcnt(0)
	s_barrier
; #define LAS __attribute__((address_space(3)))
; template <int NMAP, int VD, bool SWA> ...
;     ...
;     for (int i = 0; i < ntiles; ++i) {
;         const int t = ATT_TILE(i);
;         if (i + 1 < ntiles) { ATT_STORE((i + 1) & 1); if (i + 2 < ntiles) ATT_LOAD(ATT_TILE(i + 2)); }
;         const LAS bf16_t* kS = (const LAS bf16_t*)(lds + (i & 1) * BUFB);
;         const LAS bf16_t* vS = (const LAS bf16_t*)(lds + (i & 1) * BUFB + KBYTES);
;         bf16x8 pf[NMAP][2];
;         f32x4 sacc[NMAP][4];
; #pragma unroll
;         for (int mp = 0; mp < NMAP; ++mp) {
;             bf16x8 kf[4][2];
; #pragma unroll
;             for (int kt = 0; kt < 4; ++kt)
; #pragma unroll
;                 for (int ks = 0; ks < 2; ++ks) kf[kt][ks] = *(const LAS bf16x8*)(kS + (16 * kt + fr) * KP + mp * KMS + ks * 32 + fq * 8);
;             __builtin_amdgcn_sched_barrier(0);
; #pragma unroll
;             for (int kt = 0; kt < 4; ++kt) sacc[mp][kt] = __builtin_amdgcn_mfma_f32_16x16x32_bf16(kf[kt][0], qf[mp][0], negm[mp], 0, 0, 0);
; #pragma unroll
;             for (int kt = 0; kt < 4; ++kt) sacc[mp][kt] = __builtin_amdgcn_mfma_f32_16x16x32_bf16(kf[kt][1], qf[mp][1], sacc[mp][kt], 0, 0, 0);
;         }
;         bf16x8 va[4];
;     ...
; #pragma unroll
;         for (int i2 = 0; i2 < 4; ++i2) ATT_LDV(va[i2], i2);
;         if (SWA && t >= 4) {
;             const int dq = qp0 + 16 * w + fr - (64 * (t - 4) + 4 * fq);
; #pragma unroll
;             for (int kt = 0; kt < 4; ++kt)
; #pragma unroll
;                 for (int r = 0; r < 4; ++r) { const int d = dq - 16 * kt - r; if (d > 128 || d < -128) {
; #pragma unroll
;                     for (int mp = 0; mp < NMAP; ++mp) sacc[mp][kt][r] = -INFINITY; } }
;         }
;         float mx[NMAP];
; #pragma unroll
;         for (int mp = 0; mp < NMAP; ++mp) {
;             float v = fmax2(fmax2(sacc[mp][0][0], sacc[mp][0][1]), fmax2(sacc[mp][0][2], sacc[mp][0][3]));
; #pragma unroll
;             for (int kt = 1; kt < 4; ++kt) v = fmax2(v, fmax2(fmax2(sacc[mp][kt][0], sacc[mp][kt][1]), fmax2(sacc[mp][kt][2], sacc[mp][kt][3])));
;             mx[mp] = v;
;         }
; #pragma unroll
;         for (int mp = 0; mp < NMAP; ++mp) mx[mp] = fmax2(mx[mp], __shfl_xor(mx[mp], 16));
; #pragma unroll
;         for (int mp = 0; mp < NMAP; ++mp) mx[mp] = fmax2(mx[mp], __shfl_xor(mx[mp], 32));
; #pragma unroll
;         for (int mp = 0; mp < NMAP; ++mp) {
	s_waitcnt vmcnt(3)
	ds_write_b128 v34, v[236:239] offset:36864
	s_waitcnt vmcnt(2)
	ds_write_b128 v35, v[240:243] offset:36864
	s_waitcnt vmcnt(1)
	ds_write_b128 v34, v[244:247] offset:55296
	s_waitcnt vmcnt(0)
	ds_write_b128 v35, v[248:251] offset:55296
	v_lshl_add_u64 v[18:19], v[58:59], 0, s[34:35]
	v_lshl_add_u64 v[20:21], s[10:11], 0, v[18:19]
	v_lshl_add_u64 v[18:19], s[8:9], 0, v[18:19]
	v_lshl_add_u64 v[20:21], v[20:21], 0, v[60:61]
	v_lshl_add_u64 v[18:19], v[18:19], 0, v[60:61]
	global_load_dwordx4 v[86:89], v[20:21], off
	global_load_dwordx4 v[98:101], v[18:19], off
	v_lshl_add_u64 v[20:21], v[94:95], 0, s[34:35]
	v_lshl_add_u64 v[22:23], s[10:11], 0, v[20:21]
	v_lshl_add_u64 v[18:19], s[8:9], 0, v[20:21]
	v_lshl_add_u64 v[22:23], v[22:23], 0, v[96:97]
	v_lshl_add_u64 v[18:19], v[18:19], 0, v[96:97]
	global_load_dwordx4 v[90:93], v[22:23], off
	global_load_dwordx4 v[102:105], v[18:19], off
	ds_read_b128 v[18:21], v57
	ds_read_b128 v[22:25], v57 offset:64
	ds_read_b128 v[26:29], v57 offset:4608
	ds_read_b128 v[30:33], v57 offset:4672
	ds_read_b128 v[34:37], v57 offset:9216
	ds_read_b128 v[38:41], v57 offset:9280
	ds_read_b128 v[42:45], v57 offset:13824
	ds_read_b128 v[46:49], v57 offset:13888
	s_waitcnt lgkmcnt(7)
	v_mfma_f32_16x16x32_bf16 v[18:21], v[18:21], v[14:17], 0
	s_waitcnt lgkmcnt(5)
	v_mfma_f32_16x16x32_bf16 v[26:29], v[26:29], v[14:17], 0
	s_waitcnt lgkmcnt(3)
	v_mfma_f32_16x16x32_bf16 v[34:37], v[34:37], v[14:17], 0
	s_waitcnt lgkmcnt(1)
	v_mfma_f32_16x16x32_bf16 v[42:45], v[42:45], v[14:17], 0
	v_mfma_f32_16x16x32_bf16 v[18:21], v[22:25], v[10:13], v[18:21]
	v_mfma_f32_16x16x32_bf16 v[24:27], v[30:33], v[10:13], v[26:29]
	v_mfma_f32_16x16x32_bf16 v[28:31], v[38:41], v[10:13], v[34:37]
	s_waitcnt lgkmcnt(0)
	v_mfma_f32_16x16x32_bf16 v[32:35], v[46:49], v[10:13], v[42:45]
	s_nop 0
	ds_read_b128 v[36:39], v57 offset:128
	s_nop 0
	ds_read_b128 v[40:43], v57 offset:192
	ds_read_b128 v[44:47], v57 offset:4736
	ds_read_b128 v[48:51], v57 offset:4800
	ds_read_b128 v[52:55], v57 offset:9344
	ds_read_b128 v[62:65], v57 offset:9408
	ds_read_b128 v[66:69], v57 offset:13952
	ds_read_b128 v[70:73], v57 offset:14016
	v_lshlrev_b32_e32 v181, 1, v56
	v_med3_f32 v23, v18, v19, s27
	v_med3_f32 v56, v20, v21, s27
	s_waitcnt lgkmcnt(7)
	v_mfma_f32_16x16x32_bf16 v[36:39], v[36:39], v[6:9], 0
	v_med3_f32 v23, v23, v56, s27
	v_med3_f32 v56, v24, v25, s27
	v_med3_f32 v57, v26, v27, s27
	v_med3_f32 v56, v56, v57, s27
	s_waitcnt lgkmcnt(5)
	v_mfma_f32_16x16x32_bf16 v[44:47], v[44:47], v[6:9], 0
	v_med3_f32 v23, v23, v56, s27
	v_med3_f32 v56, v28, v29, s27
	v_med3_f32 v57, v30, v31, s27
	v_med3_f32 v56, v56, v57, s27
	v_med3_f32 v23, v23, v56, s27
	v_med3_f32 v56, v32, v33, s27
	v_mfma_f32_16x16x32_bf16 v[36:39], v[40:43], v[2:5], v[36:39]
	v_med3_f32 v40, v34, v35, s27
	v_med3_f32 v40, v56, v40, s27
	v_med3_f32 v23, v23, v40, s27
	s_waitcnt lgkmcnt(3)
	v_mfma_f32_16x16x32_bf16 v[52:55], v[52:55], v[6:9], 0
	v_add3_u32 v22, 0, v0, v181
	v_mad_i64_i32 v[58:59], s[8:9], s14, v192, v[58:59]
	v_mfma_f32_16x16x32_bf16 v[40:43], v[48:51], v[2:5], v[44:47]
	v_lshl_add_u64 v[58:59], v[58:59], 0, v[60:61]
	s_and_b64 s[8:9], s[0:1], exec
	s_cselect_b32 s10, 1, 33
	s_waitcnt lgkmcnt(1)
	v_mfma_f32_16x16x32_bf16 v[66:69], v[66:69], v[6:9], 0
	v_med3_f32 v44, v36, v37, s27
	v_med3_f32 v45, v38, v39, s27
	v_med3_f32 v56, v44, v45, s27
	v_mfma_f32_16x16x32_bf16 v[44:47], v[62:65], v[2:5], v[52:55]
	v_med3_f32 v48, v40, v41, s27
	v_med3_f32 v49, v42, v43, s27
	s_lshl_b32 s11, s10, 14
	v_med3_f32 v52, v48, v49, s27
	s_waitcnt lgkmcnt(0)
	v_mfma_f32_16x16x32_bf16 v[48:51], v[70:73], v[2:5], v[66:69]
	s_nop 1
	v_med3_f32 v53, v44, v45, s27
	v_med3_f32 v54, v46, v47, s27
	v_med3_f32 v52, v56, v52, s27
	v_med3_f32 v53, v53, v54, s27
	v_med3_f32 v52, v52, v53, s27
	s_nop 0
	v_med3_f32 v53, v48, v49, s27
	v_med3_f32 v54, v50, v51, s27
	v_med3_f32 v53, v53, v54, s27
	v_med3_f32 v54, v52, v53, s27
	ds_bpermute_b32 v55, v179, v23
	ds_bpermute_b32 v56, v179, v54
	ds_read_b64_tr_b16 v[52:53], v22 offset:18432
	ds_read_b64_tr_b16 v[62:63], v22 offset:18464
	ds_read_b64_tr_b16 v[66:67], v22 offset:18496
	ds_read_b64_tr_b16 v[70:71], v22 offset:18528
	s_waitcnt lgkmcnt(5)
	v_med3_f32 v23, v23, v55, s27
	s_waitcnt lgkmcnt(4)
	v_med3_f32 v56, v54, v56, s27
	ds_bpermute_b32 v57, v180, v23
	ds_bpermute_b32 v74, v180, v56
	ds_read_b64_tr_b16 v[54:55], v22 offset:23040
	ds_read_b64_tr_b16 v[64:65], v22 offset:23072
	ds_read_b64_tr_b16 v[68:69], v22 offset:23104
	ds_read_b64_tr_b16 v[72:73], v22 offset:23136
	s_waitcnt lgkmcnt(5)
	v_med3_f32 v23, v23, v57, s27
	s_waitcnt lgkmcnt(4)
	v_med3_f32 v109, v56, v74, s27
	v_sub_f32_e32 v35, v35, v23
	v_sub_f32_e32 v34, v34, v23
	v_sub_f32_e32 v33, v33, v23
	v_sub_f32_e32 v32, v32, v23
	v_sub_f32_e32 v31, v31, v23
	v_sub_f32_e32 v30, v30, v23
	v_sub_f32_e32 v29, v29, v23
	v_sub_f32_e32 v28, v28, v23
	v_sub_f32_e32 v27, v27, v23
	v_sub_f32_e32 v26, v26, v23
	v_sub_f32_e32 v25, v25, v23
	v_sub_f32_e32 v24, v24, v23
	v_sub_f32_e32 v21, v21, v23
	v_sub_f32_e32 v20, v20, v23
	v_sub_f32_e32 v19, v19, v23
	v_sub_f32_e32 v18, v18, v23
	v_exp_f32_e32 v111, v28
	v_exp_f32_e32 v156, v29
	v_exp_f32_e32 v157, v30
	v_exp_f32_e32 v164, v31
	v_exp_f32_e32 v165, v32
	v_exp_f32_e32 v166, v33
	v_exp_f32_e32 v167, v34
	v_exp_f32_e32 v183, v35
	v_sub_f32_e32 v28, v43, v109
	v_sub_f32_e32 v29, v42, v109
	v_sub_f32_e32 v30, v41, v109
	v_sub_f32_e32 v31, v40, v109
	v_sub_f32_e32 v32, v39, v109
	v_sub_f32_e32 v33, v38, v109
	v_sub_f32_e32 v34, v37, v109
	v_sub_f32_e32 v35, v36, v109
	v_exp_f32_e32 v56, v18
	v_exp_f32_e32 v57, v19
	v_exp_f32_e32 v74, v20
	v_exp_f32_e32 v75, v21
	v_exp_f32_e32 v76, v24
	v_exp_f32_e32 v106, v25
	v_exp_f32_e32 v108, v26
	v_exp_f32_e32 v110, v27
	v_cvt_pk_bf16_f32 v24, v56, v57
	v_cvt_pk_bf16_f32 v25, v74, v75
	v_cvt_pk_bf16_f32 v26, v76, v106
	v_cvt_pk_bf16_f32 v27, v108, v110
	v_cvt_pk_bf16_f32 v18, v111, v156
	v_cvt_pk_bf16_f32 v19, v157, v164
	v_cvt_pk_bf16_f32 v20, v165, v166
	v_cvt_pk_bf16_f32 v21, v167, v183
	v_sub_f32_e32 v77, v51, v109
	v_sub_f32_e32 v78, v50, v109
	v_sub_f32_e32 v79, v49, v109
	v_exp_f32_e32 v202, v35
	v_exp_f32_e32 v203, v34
	v_exp_f32_e32 v212, v33
	v_exp_f32_e32 v213, v32
	v_exp_f32_e32 v214, v31
	v_exp_f32_e32 v215, v30
	v_exp_f32_e32 v216, v29
	v_exp_f32_e32 v217, v28
	v_cvt_pk_bf16_f32 v28, v202, v203
	s_waitcnt lgkmcnt(3)
; __device__ __forceinline__ unsigned cvt_pk_bf16(float lo, float hi) { unsigned r; asm volatile("v_cvt_pk_bf16_f32 %0, %1, %2" : "=v"(r) : "v"(lo), "v"(hi)); return r; }
; template <int NMAP, int VD, bool SWA> ...
;     ...
;                 for (int r = 0; r < 4; ++r) { const float p = __builtin_amdgcn_exp2f(sacc[mp][kt][r]); sacc[mp][kt][r] = p; ps += p; }
;             lsum[mp] += ps;
; #pragma unroll
;             for (int s2 = 0; s2 < 2; ++s2) {
;                 u32x4 pk; pk.x = cvt_pk_bf16(sacc[mp][2 * s2][0], sacc[mp][2 * s2][1]); pk.y = cvt_pk_bf16(sacc[mp][2 * s2][2], sacc[mp][2 * s2][3]);
;                 pk.z = cvt_pk_bf16(sacc[mp][2 * s2 + 1][0], sacc[mp][2 * s2 + 1][1]); pk.w = cvt_pk_bf16(sacc[mp][2 * s2 + 1][2], sacc[mp][2 * s2 + 1][3]);
;                 pf[mp][s2] = __builtin_bit_cast(bf16x8, pk);
;             }
;         }
; #pragma unroll
;         for (int idx = 0; idx < 2 * NET; ++idx) {
;             const int et = idx % NET, s2 = idx / NET;
;             const bf16x8 cur = va[idx & 3];
;             if (idx + 4 < 2 * NET) ATT_LDV(va[idx & 3], idx + 4);
; #pragma unroll
;             for (int mp = 0; mp < NMAP; ++mp) oacc[mp][et] = __builtin_amdgcn_mfma_f32_16x16x32_bf16(cur, pf[mp][s2], oacc[mp][et], 0, 0, 0);
;         }
;     ...
;         __syncthreads();
	v_mfma_f32_16x16x32_bf16 v[32:35], v[52:55], v[24:27], 0
	v_cvt_pk_bf16_f32 v29, v212, v213
	v_cvt_pk_bf16_f32 v30, v214, v215
	v_cvt_pk_bf16_f32 v31, v216, v217
	v_sub_f32_e32 v49, v46, v109
	v_mfma_f32_16x16x32_bf16 v[36:39], v[52:55], v[28:31], 0
	v_sub_f32_e32 v52, v48, v109
	v_sub_f32_e32 v48, v47, v109
	v_sub_f32_e32 v50, v45, v109
	v_sub_f32_e32 v44, v44, v109
	s_waitcnt lgkmcnt(2)
	v_mfma_f32_16x16x32_bf16 v[40:43], v[62:65], v[24:27], 0
	v_exp_f32_e32 v218, v44
	v_exp_f32_e32 v219, v50
	v_exp_f32_e32 v220, v49
	v_mfma_f32_16x16x32_bf16 v[44:47], v[62:65], v[28:31], 0
	v_exp_f32_e32 v221, v48
	v_exp_f32_e32 v222, v52
	v_exp_f32_e32 v223, v79
	v_exp_f32_e32 v224, v78
	v_exp_f32_e32 v225, v77
	v_cvt_pk_bf16_f32 v112, v218, v219
	v_cvt_pk_bf16_f32 v113, v220, v221
	v_cvt_pk_bf16_f32 v114, v222, v223
	v_cvt_pk_bf16_f32 v115, v224, v225
	ds_read_b64_tr_b16 v[64:65], v22 offset:23168
	ds_read_b64_tr_b16 v[62:63], v22 offset:18560
	s_waitcnt lgkmcnt(3)
	v_mfma_f32_16x16x32_bf16 v[48:51], v[66:69], v[24:27], 0
	v_mfma_f32_16x16x32_bf16 v[52:55], v[66:69], v[28:31], 0
	ds_read_b64_tr_b16 v[68:69], v22 offset:23200
	ds_read_b64_tr_b16 v[66:67], v22 offset:18592
	s_waitcnt lgkmcnt(2)
	v_mfma_f32_16x16x32_bf16 v[124:127], v[62:65], v[24:27], 0
	v_mfma_f32_16x16x32_bf16 v[128:131], v[62:65], v[28:31], 0
	ds_read_b64_tr_b16 v[62:63], v22 offset:18624
	ds_read_b64_tr_b16 v[64:65], v22 offset:23232
	s_waitcnt lgkmcnt(2)
	v_mfma_f32_16x16x32_bf16 v[132:135], v[66:69], v[24:27], 0
	v_mfma_f32_16x16x32_bf16 v[136:139], v[66:69], v[28:31], 0
	ds_read_b64_tr_b16 v[66:67], v22 offset:18656
	s_waitcnt lgkmcnt(1)
	v_mfma_f32_16x16x32_bf16 v[140:143], v[62:65], v[24:27], 0
	v_mfma_f32_16x16x32_bf16 v[144:147], v[62:65], v[28:31], 0
	ds_read_b64_tr_b16 v[68:69], v22 offset:23264
	ds_read_b64_tr_b16 v[62:63], v22 offset:27648
	v_mfma_f32_16x16x32_bf16 v[116:119], v[70:73], v[24:27], 0
	s_waitcnt lgkmcnt(1)
	v_mfma_f32_16x16x32_bf16 v[148:151], v[66:69], v[24:27], 0
	ds_read_b64_tr_b16 v[64:65], v22 offset:32256
	ds_read_b64_tr_b16 v[24:25], v22 offset:27680
	ds_read_b64_tr_b16 v[152:153], v22 offset:27712
	s_waitcnt lgkmcnt(2)
	v_mfma_f32_16x16x32_bf16 v[78:81], v[62:65], v[18:21], v[32:35]
	s_nop 2
	v_add_f32_e32 v32, 0, v56
	v_add_f32_e32 v32, v57, v32
	v_add_f32_e32 v32, v74, v32
	v_add_f32_e32 v32, v75, v32
	v_mfma_f32_16x16x32_bf16 v[120:123], v[70:73], v[28:31], 0
	v_add_f32_e32 v32, v76, v32
	v_add_f32_e32 v32, v106, v32
	v_add_f32_e32 v32, v108, v32
	v_mfma_f32_16x16x32_bf16 v[168:171], v[66:69], v[28:31], 0
	ds_read_b64_tr_b16 v[28:29], v22 offset:27744
	ds_read_b64_tr_b16 v[26:27], v22 offset:32288
	ds_read_b64_tr_b16 v[154:155], v22 offset:32320
	ds_read_b64_tr_b16 v[30:31], v22 offset:32352
	v_add_f32_e32 v32, v110, v32
	s_waitcnt lgkmcnt(2)
	v_mfma_f32_16x16x32_bf16 v[74:77], v[24:27], v[18:21], v[40:43]
	v_mfma_f32_16x16x32_bf16 v[70:73], v[24:27], v[112:115], v[44:47]
	v_add_f32_e32 v24, v111, v32
	v_add_f32_e32 v24, v156, v24
	v_add_f32_e32 v24, v157, v24
	v_add_f32_e32 v24, v164, v24
	v_add_f32_e32 v24, v165, v24
	v_add_f32_e32 v24, v166, v24
	v_mfma_f32_16x16x32_bf16 v[82:85], v[62:65], v[112:115], v[36:39]
	s_nop 2
	v_add_f32_e32 v36, v167, v24
	s_waitcnt lgkmcnt(1)
	v_mfma_f32_16x16x32_bf16 v[66:69], v[152:155], v[18:21], v[48:51]
	ds_read_b64_tr_b16 v[24:25], v22 offset:27776
	ds_read_b64_tr_b16 v[26:27], v22 offset:32384
	v_mfma_f32_16x16x32_bf16 v[62:65], v[152:155], v[112:115], v[52:55]
	s_waitcnt lgkmcnt(2)
	v_mfma_f32_16x16x32_bf16 v[54:57], v[28:31], v[18:21], v[116:119]
	ds_read_b64_tr_b16 v[32:33], v22 offset:27808
	s_nop 1
	ds_read_b64_tr_b16 v[116:117], v22 offset:27840
	ds_read_b64_tr_b16 v[152:153], v22 offset:27872
	ds_read_b64_tr_b16 v[34:35], v22 offset:32416
	ds_read_b64_tr_b16 v[118:119], v22 offset:32448
	ds_read_b64_tr_b16 v[154:155], v22 offset:32480
	v_add_f32_e32 v22, v183, v36
	v_pk_add_f32 v[166:167], v[22:23], 0 op_sel_hi:[1,0]
	v_add_f32_e32 v22, 0, v202
	v_add_f32_e32 v22, v203, v22
	v_add_f32_e32 v22, v212, v22
	v_add_f32_e32 v22, v213, v22
	v_add_f32_e32 v22, v214, v22
	v_add_f32_e32 v22, v215, v22
	v_add_f32_e32 v22, v216, v22
	v_add_f32_e32 v22, v217, v22
	v_add_f32_e32 v22, v218, v22
	v_add_f32_e32 v22, v219, v22
	v_add_f32_e32 v22, v220, v22
	v_add_f32_e32 v22, v221, v22
	v_add_f32_e32 v22, v222, v22
	v_add_f32_e32 v22, v223, v22
	v_add_f32_e32 v108, v224, v22
	v_mfma_f32_16x16x32_bf16 v[50:53], v[28:31], v[112:115], v[120:123]
	v_add_f32_e32 v108, v225, v108
	v_pk_add_f32 v[164:165], v[108:109], 0 op_sel_hi:[1,0]
	v_xor_b32_e32 v106, 0x80000000, v167
	s_waitcnt lgkmcnt(6)
	v_mfma_f32_16x16x32_bf16 v[46:49], v[24:27], v[18:21], v[124:127]
	v_xor_b32_e32 v110, 0x80000000, v165
	v_lshlrev_b32_e32 v183, 1, v107
	v_mov_b32_e32 v111, v110
	v_mfma_f32_16x16x32_bf16 v[42:45], v[24:27], v[112:115], v[128:131]
	v_mov_b32_e32 v107, v106
	v_mov_b32_e32 v108, v106
	v_mov_b32_e32 v109, v106
	s_waitcnt lgkmcnt(2)
	v_mfma_f32_16x16x32_bf16 v[38:41], v[32:35], v[18:21], v[132:135]
	s_waitcnt lgkmcnt(0)
	s_barrier
	v_mfma_f32_16x16x32_bf16 v[34:37], v[32:35], v[112:115], v[136:139]
	v_mfma_f32_16x16x32_bf16 v[30:33], v[116:119], v[18:21], v[140:143]
	v_mfma_f32_16x16x32_bf16 v[26:29], v[116:119], v[112:115], v[144:147]
	v_mfma_f32_16x16x32_bf16 v[22:25], v[152:155], v[18:21], v[148:151]
	v_mfma_f32_16x16x32_bf16 v[18:21], v[152:155], v[112:115], v[168:171]
	v_mov_b32_e32 v112, v110
	v_mov_b32_e32 v113, v110
	s_nop 0
	v_lshl_add_u64 v[168:169], s[4:5], 0, v[58:59]
	v_mad_i64_i32 v[58:59], s[8:9], s14, v192, v[94:95]
	v_lshl_add_u64 v[58:59], v[58:59], 0, v[96:97]
	v_lshl_add_u64 v[170:171], s[4:5], 0, v[58:59]
	s_mov_b64 s[8:9], 0
	v_subrev_u32_e32 v236, s4, v168
	v_subrev_u32_e32 v237, s4, v170
	v_add_u32_e32 v238, 0x1200000, v236
	v_add_u32_e32 v239, 0x1200000, v237
	s_add_u32 s34, s4, 0x1810c000
	s_addc_u32 s35, s5, 0
	s_branch .LBB0_125

; #define PG8_STAGE(bufoff, gbase, voff) do { _Pragma("unroll") for (int _i = 0; _i < 2; ++_i) \
;         __builtin_amdgcn_global_load_lds((const unsigned*)((const char*)(gbase) + (voff)[_i]), (LAS unsigned*)(lds + (bufoff) + ldsw + _i * 8192), 16, 0, 0); } while (0)
; #define PG8_LDA(dst, b, h) do { _Pragma("unroll") for (int m = 0; m < 4; ++m) _Pragma("unroll") for (int k = 0; k < 2; ++k) dst[m][k] = *(const LAS bf16x8*)(lds + PG8_SA(b, h) + aoff + m * 2048 + k * 1024); } while (0)
; #define PG8_LDB(dst, b, h) do { _Pragma("unroll") for (int n = 0; n < 2; ++n) _Pragma("unroll") for (int k = 0; k < 2; ++k) dst[n][k] = *(const LAS bf16x8*)(lds + PG8_SB(b, h) + boff + n * 2048 + k * 1024); } while (0)
; #define PG8_MMA(ai, bj, At, Bt) do { __builtin_amdgcn_s_setprio(1); _Pragma("unroll") for (int m = 0; m < 4; ++m) _Pragma("unroll") for (int n = 0; n < 2; ++n) _Pragma("unroll") for (int k = 0; k < 2; ++k) \
;         acc[ai][bj][m][n] = __builtin_amdgcn_mfma_f32_16x16x32_bf16(Bt[n][k], At[m][k], acc[ai][bj][m][n], 0, 0, 0); __builtin_amdgcn_s_setprio(0); } while (0)
; #define PG8_WAIT_V(n) asm volatile("s_waitcnt vmcnt(" #n ")" ::: "memory")
; #define PG8_WAIT_L(n) asm volatile("s_waitcnt lgkmcnt(" #n ")" ::: "memory")
; #define PG8_BAR __builtin_amdgcn_s_barrier()
; #define PG8_SCHED __builtin_amdgcn_sched_barrier(0)
; template <class Epi, class Sched, bool ALIGN_EPI = false, bool SP2 = false>
; __device__ __forceinline__ void gemm_phase(LAS unsigned char* lds, const Gemm g, const Sched& S, const Epi& E, const int tid) {
;     ...
;             PG8_LDB(B0, 0, 0); PG8_LDB(B1, 0, 1); PG8_SCHED; PG8_LDA(At, 0, 0); PG8_STAGE(PG8_SA(1, 1), a1 + hstep, voffA);
;             PG8_WAIT_V(8); PG8_WAIT_L(0); PG8_BAR; PG8_MMA(0, 0, At, B0); PG8_MMA(0, 1, At, B1); PG8_BAR; PG8_SCHED;
;             PG8_LDA(At, 0, 1); PG8_STAGE(PG8_SB(0, 0), b2, voffB); PG8_STAGE(PG8_SB(0, 1), b2 + hstep, voffB); PG8_STAGE(PG8_SA(0, 0), a2, voffA);
.LBB0_531:
	s_add_i32 s54, s28, 2
	s_add_u32 s55, s24, 0x80
	s_addc_u32 s29, s25, 0
	s_add_i32 s57, 0, 0x10000
	s_cmp_eq_u32 s21, s28
	s_cselect_b32 s29, s23, s29
	s_cselect_b32 s28, s22, s55
	v_add_u32_e32 v140, s57, v143
	s_cselect_b32 s61, s1, s53
	s_cselect_b32 s60, s0, s52
	s_add_i32 s55, 0, 0x14000
	ds_read_b128 v[146:149], v140
	ds_read_b128 v[150:153], v140 offset:1024
	ds_read_b128 v[154:157], v140 offset:2048
	ds_read_b128 v[160:163], v140 offset:3072
	v_add_u32_e32 v140, s55, v143
	ds_read_b128 v[164:167], v140
	ds_read_b128 v[168:171], v140 offset:1024
	ds_read_b128 v[172:175], v140 offset:2048
	ds_read_b128 v[176:179], v140 offset:3072
	v_lshl_add_u64 v[140:141], s[24:25], 0, v[138:139]
	s_add_i32 m0, s31, 0xc000
	ds_read_b128 v[180:183], v145
	ds_read_b128 v[208:211], v145 offset:1024
	ds_read_b128 v[212:215], v145 offset:2048
	ds_read_b128 v[216:219], v145 offset:3072
	ds_read_b128 v[220:223], v145 offset:4096
	ds_read_b128 v[224:227], v145 offset:5120
	ds_read_b128 v[228:231], v145 offset:6144
	ds_read_b128 v[232:235], v145 offset:7168
	global_load_lds_dwordx4 v[140:141], off
	v_lshl_add_u64 v[140:141], s[24:25], 0, v[136:137]
	s_add_i32 m0, s31, 0xe000
	s_nop 0
	global_load_lds_dwordx4 v[140:141], off
	s_waitcnt vmcnt(8)
	s_waitcnt lgkmcnt(0)
	s_barrier
	s_setprio 1
	s_waitcnt lgkmcnt(0)
	v_mfma_f32_16x16x32_bf16 v[126:129], v[146:149], v[180:183], v[126:129]
	v_mfma_f32_16x16x32_bf16 v[122:125], v[154:157], v[180:183], v[122:125]
	v_mfma_f32_16x16x32_bf16 v[118:121], v[146:149], v[212:215], v[118:121]
	v_mfma_f32_16x16x32_bf16 v[110:113], v[154:157], v[212:215], v[110:113]
	v_mfma_f32_16x16x32_bf16 v[102:105], v[146:149], v[220:223], v[102:105]
	v_mfma_f32_16x16x32_bf16 v[94:97], v[154:157], v[220:223], v[94:97]
	v_mfma_f32_16x16x32_bf16 v[86:89], v[146:149], v[228:231], v[86:89]
	v_mfma_f32_16x16x32_bf16 v[78:81], v[154:157], v[228:231], v[78:81]
	v_mfma_f32_16x16x32_bf16 v[126:129], v[150:153], v[208:211], v[126:129]
	v_mfma_f32_16x16x32_bf16 v[122:125], v[160:163], v[208:211], v[122:125]
	v_mfma_f32_16x16x32_bf16 v[118:121], v[150:153], v[216:219], v[118:121]
	v_mfma_f32_16x16x32_bf16 v[110:113], v[160:163], v[216:219], v[110:113]
	v_mfma_f32_16x16x32_bf16 v[102:105], v[150:153], v[224:227], v[102:105]
	v_mfma_f32_16x16x32_bf16 v[94:97], v[160:163], v[224:227], v[94:97]
	v_mfma_f32_16x16x32_bf16 v[86:89], v[150:153], v[232:235], v[86:89]
	v_mfma_f32_16x16x32_bf16 v[78:81], v[160:163], v[232:235], v[78:81]
	s_setprio 0
	s_setprio 1
	v_mfma_f32_16x16x32_bf16 v[114:117], v[164:167], v[180:183], v[114:117]
	v_mfma_f32_16x16x32_bf16 v[106:109], v[172:175], v[180:183], v[106:109]
	v_mfma_f32_16x16x32_bf16 v[98:101], v[164:167], v[212:215], v[98:101]
	v_mfma_f32_16x16x32_bf16 v[90:93], v[172:175], v[212:215], v[90:93]
	v_mfma_f32_16x16x32_bf16 v[82:85], v[164:167], v[220:223], v[82:85]
	v_mfma_f32_16x16x32_bf16 v[74:77], v[172:175], v[220:223], v[74:77]
	v_mfma_f32_16x16x32_bf16 v[70:73], v[164:167], v[228:231], v[70:73]
	v_mfma_f32_16x16x32_bf16 v[66:69], v[172:175], v[228:231], v[66:69]
	v_mfma_f32_16x16x32_bf16 v[114:117], v[168:171], v[208:211], v[114:117]
	v_mfma_f32_16x16x32_bf16 v[106:109], v[176:179], v[208:211], v[106:109]
	v_mfma_f32_16x16x32_bf16 v[98:101], v[168:171], v[216:219], v[98:101]
	v_mfma_f32_16x16x32_bf16 v[90:93], v[176:179], v[216:219], v[90:93]
	v_mfma_f32_16x16x32_bf16 v[82:85], v[168:171], v[224:227], v[82:85]
	v_mfma_f32_16x16x32_bf16 v[74:77], v[176:179], v[224:227], v[74:77]
	v_mfma_f32_16x16x32_bf16 v[70:73], v[168:171], v[232:235], v[70:73]
	v_mfma_f32_16x16x32_bf16 v[66:69], v[176:179], v[232:235], v[66:69]
	s_setprio 0
	s_barrier
	s_add_i32 s57, s57, s26
	v_lshl_add_u64 v[140:141], s[60:61], 0, v[0:1]
	s_mov_b32 m0, s57
	ds_read_b128 v[180:183], v145 offset:16384
	ds_read_b128 v[208:211], v145 offset:17408
	ds_read_b128 v[212:215], v145 offset:18432
	ds_read_b128 v[216:219], v145 offset:19456
	ds_read_b128 v[220:223], v145 offset:20480
	ds_read_b128 v[224:227], v145 offset:21504
	ds_read_b128 v[228:231], v145 offset:22528
	ds_read_b128 v[232:235], v145 offset:23552
	global_load_lds_dwordx4 v[140:141], off
	s_add_i32 m0, s57, 0x2000
	v_lshl_add_u64 v[236:237], s[60:61], 0, v[130:131]
	s_add_u32 s60, s60, s16
	s_addc_u32 s61, s61, 0
	s_add_i32 s55, s55, s26
	global_load_lds_dwordx4 v[236:237], off
	v_lshl_add_u64 v[238:239], s[60:61], 0, v[0:1]
	s_mov_b32 m0, s55
	v_lshl_add_u64 v[240:241], s[60:61], 0, v[130:131]
	global_load_lds_dwordx4 v[238:239], off
	s_add_i32 m0, s55, 0x2000
	v_lshl_add_u64 v[242:243], s[28:29], 0, v[134:135]
	global_load_lds_dwordx4 v[240:241], off
	s_mov_b32 m0, s31
	v_lshl_add_u64 v[244:245], s[28:29], 0, v[132:133]
	global_load_lds_dwordx4 v[242:243], off
	s_mov_b32 m0, s33
	s_nop 0
	global_load_lds_dwordx4 v[244:245], off
	s_waitcnt vmcnt(8)
	s_waitcnt lgkmcnt(0)
	s_barrier
; #define PG8_STAGE(bufoff, gbase, voff) do { _Pragma("unroll") for (int _i = 0; _i < 2; ++_i) \
;         __builtin_amdgcn_global_load_lds((const unsigned*)((const char*)(gbase) + (voff)[_i]), (LAS unsigned*)(lds + (bufoff) + ldsw + _i * 8192), 16, 0, 0); } while (0)
; #define PG8_LDA(dst, b, h) do { _Pragma("unroll") for (int m = 0; m < 4; ++m) _Pragma("unroll") for (int k = 0; k < 2; ++k) dst[m][k] = *(const LAS bf16x8*)(lds + PG8_SA(b, h) + aoff + m * 2048 + k * 1024); } while (0)
; #define PG8_LDB(dst, b, h) do { _Pragma("unroll") for (int n = 0; n < 2; ++n) _Pragma("unroll") for (int k = 0; k < 2; ++k) dst[n][k] = *(const LAS bf16x8*)(lds + PG8_SB(b, h) + boff + n * 2048 + k * 1024); } while (0)
; #define PG8_MMA(ai, bj, At, Bt) do { __builtin_amdgcn_s_setprio(1); _Pragma("unroll") for (int m = 0; m < 4; ++m) _Pragma("unroll") for (int n = 0; n < 2; ++n) _Pragma("unroll") for (int k = 0; k < 2; ++k) \
;         acc[ai][bj][m][n] = __builtin_amdgcn_mfma_f32_16x16x32_bf16(Bt[n][k], At[m][k], acc[ai][bj][m][n], 0, 0, 0); __builtin_amdgcn_s_setprio(0); } while (0)
; #define PG8_WAIT_V(n) asm volatile("s_waitcnt vmcnt(" #n ")" ::: "memory")
; #define PG8_WAIT_L(n) asm volatile("s_waitcnt lgkmcnt(" #n ")" ::: "memory")
; #define PG8_BAR __builtin_amdgcn_s_barrier()
; #define PG8_SCHED __builtin_amdgcn_sched_barrier(0)
; template <class Epi, class Sched, bool ALIGN_EPI = false, bool SP2 = false>
; __device__ __forceinline__ void gemm_phase(LAS unsigned char* lds, const Gemm g, const Sched& S, const Epi& E, const int tid) {
;     ...
;             PG8_WAIT_V(8); PG8_WAIT_L(0); PG8_BAR; PG8_MMA(1, 0, At, B0); PG8_MMA(1, 1, At, B1); PG8_BAR; PG8_SCHED;
;             PG8_LDB(B0, 1, 0); PG8_LDB(B1, 1, 1); PG8_SCHED; PG8_LDA(At, 1, 0); PG8_STAGE(PG8_SA(0, 1), a2 + hstep, voffA);
;             PG8_WAIT_V(8); PG8_WAIT_L(0); PG8_BAR; PG8_MMA(0, 0, At, B0); PG8_MMA(0, 1, At, B1); PG8_BAR; PG8_SCHED;
	s_setprio 1
	s_waitcnt lgkmcnt(0)
	v_mfma_f32_16x16x32_bf16 v[62:65], v[146:149], v[180:183], v[62:65]
	v_mfma_f32_16x16x32_bf16 v[58:61], v[154:157], v[180:183], v[58:61]
	v_mfma_f32_16x16x32_bf16 v[54:57], v[146:149], v[212:215], v[54:57]
	v_mfma_f32_16x16x32_bf16 v[46:49], v[154:157], v[212:215], v[46:49]
	v_mfma_f32_16x16x32_bf16 v[38:41], v[146:149], v[220:223], v[38:41]
	v_mfma_f32_16x16x32_bf16 v[30:33], v[154:157], v[220:223], v[30:33]
	v_mfma_f32_16x16x32_bf16 v[22:25], v[146:149], v[228:231], v[22:25]
	v_mfma_f32_16x16x32_bf16 v[14:17], v[154:157], v[228:231], v[14:17]
	v_mfma_f32_16x16x32_bf16 v[62:65], v[150:153], v[208:211], v[62:65]
	v_mfma_f32_16x16x32_bf16 v[58:61], v[160:163], v[208:211], v[58:61]
	v_mfma_f32_16x16x32_bf16 v[54:57], v[150:153], v[216:219], v[54:57]
	v_mfma_f32_16x16x32_bf16 v[46:49], v[160:163], v[216:219], v[46:49]
	v_mfma_f32_16x16x32_bf16 v[38:41], v[150:153], v[224:227], v[38:41]
	v_mfma_f32_16x16x32_bf16 v[30:33], v[160:163], v[224:227], v[30:33]
	v_mfma_f32_16x16x32_bf16 v[22:25], v[150:153], v[232:235], v[22:25]
	v_mfma_f32_16x16x32_bf16 v[14:17], v[160:163], v[232:235], v[14:17]
	s_setprio 0
	s_setprio 1
	v_mfma_f32_16x16x32_bf16 v[50:53], v[164:167], v[180:183], v[50:53]
	v_mfma_f32_16x16x32_bf16 v[42:45], v[172:175], v[180:183], v[42:45]
	v_mfma_f32_16x16x32_bf16 v[34:37], v[164:167], v[212:215], v[34:37]
	v_mfma_f32_16x16x32_bf16 v[26:29], v[172:175], v[212:215], v[26:29]
	v_mfma_f32_16x16x32_bf16 v[18:21], v[164:167], v[220:223], v[18:21]
	v_mfma_f32_16x16x32_bf16 v[10:13], v[172:175], v[220:223], v[10:13]
	v_mfma_f32_16x16x32_bf16 v[6:9], v[164:167], v[228:231], v[6:9]
	v_mfma_f32_16x16x32_bf16 v[2:5], v[172:175], v[228:231], v[2:5]
	v_mfma_f32_16x16x32_bf16 v[50:53], v[168:171], v[208:211], v[50:53]
	v_mfma_f32_16x16x32_bf16 v[42:45], v[176:179], v[208:211], v[42:45]
	v_mfma_f32_16x16x32_bf16 v[34:37], v[168:171], v[216:219], v[34:37]
	v_mfma_f32_16x16x32_bf16 v[26:29], v[176:179], v[216:219], v[26:29]
	v_mfma_f32_16x16x32_bf16 v[18:21], v[168:171], v[224:227], v[18:21]
	v_mfma_f32_16x16x32_bf16 v[10:13], v[176:179], v[224:227], v[10:13]
	v_mfma_f32_16x16x32_bf16 v[6:9], v[168:171], v[232:235], v[6:9]
	v_mfma_f32_16x16x32_bf16 v[2:5], v[176:179], v[232:235], v[2:5]
	s_setprio 0
	s_barrier
	s_add_i32 s55, 0, 0x18000
	v_add_u32_e32 v159, s55, v143
	s_add_i32 s57, 0, 0x1c000
	ds_read_b128 v[146:149], v159
	ds_read_b128 v[150:153], v159 offset:1024
	ds_read_b128 v[154:157], v159 offset:2048
	ds_read_b128 v[160:163], v159 offset:3072
	v_add_u32_e32 v159, s57, v143
	ds_read_b128 v[164:167], v159
	ds_read_b128 v[168:171], v159 offset:1024
	ds_read_b128 v[172:175], v159 offset:2048
	ds_read_b128 v[176:179], v159 offset:3072
	s_add_u32 s28, s28, s16
	s_addc_u32 s29, s29, 0
	s_mov_b32 m0, s34
	v_lshl_add_u64 v[246:247], s[28:29], 0, v[134:135]
	ds_read_b128 v[180:183], v145 offset:32768
	ds_read_b128 v[208:211], v145 offset:33792
	ds_read_b128 v[212:215], v145 offset:34816
	ds_read_b128 v[216:219], v145 offset:35840
	ds_read_b128 v[220:223], v145 offset:36864
	ds_read_b128 v[224:227], v145 offset:37888
	ds_read_b128 v[228:231], v145 offset:38912
	ds_read_b128 v[232:235], v145 offset:39936
	global_load_lds_dwordx4 v[246:247], off
	v_lshl_add_u64 v[246:247], s[28:29], 0, v[132:133]
	s_mov_b32 m0, s35
	s_nop 0
	global_load_lds_dwordx4 v[246:247], off
	s_waitcnt vmcnt(8)
	s_waitcnt lgkmcnt(0)
	s_barrier
	s_setprio 1
	s_waitcnt lgkmcnt(0)
	v_mfma_f32_16x16x32_bf16 v[126:129], v[146:149], v[180:183], v[126:129]
	v_mfma_f32_16x16x32_bf16 v[122:125], v[154:157], v[180:183], v[122:125]
	v_mfma_f32_16x16x32_bf16 v[118:121], v[146:149], v[212:215], v[118:121]
	v_mfma_f32_16x16x32_bf16 v[110:113], v[154:157], v[212:215], v[110:113]
	v_mfma_f32_16x16x32_bf16 v[102:105], v[146:149], v[220:223], v[102:105]
	v_mfma_f32_16x16x32_bf16 v[94:97], v[154:157], v[220:223], v[94:97]
	v_mfma_f32_16x16x32_bf16 v[86:89], v[146:149], v[228:231], v[86:89]
	v_mfma_f32_16x16x32_bf16 v[78:81], v[154:157], v[228:231], v[78:81]
	v_mfma_f32_16x16x32_bf16 v[126:129], v[150:153], v[208:211], v[126:129]
	v_mfma_f32_16x16x32_bf16 v[122:125], v[160:163], v[208:211], v[122:125]
	v_mfma_f32_16x16x32_bf16 v[118:121], v[150:153], v[216:219], v[118:121]
	v_mfma_f32_16x16x32_bf16 v[110:113], v[160:163], v[216:219], v[110:113]
	v_mfma_f32_16x16x32_bf16 v[102:105], v[150:153], v[224:227], v[102:105]
	v_mfma_f32_16x16x32_bf16 v[94:97], v[160:163], v[224:227], v[94:97]
	v_mfma_f32_16x16x32_bf16 v[86:89], v[150:153], v[232:235], v[86:89]
	v_mfma_f32_16x16x32_bf16 v[78:81], v[160:163], v[232:235], v[78:81]
	s_setprio 0
	s_setprio 1
	v_mfma_f32_16x16x32_bf16 v[114:117], v[164:167], v[180:183], v[114:117]
	v_mfma_f32_16x16x32_bf16 v[106:109], v[172:175], v[180:183], v[106:109]
	v_mfma_f32_16x16x32_bf16 v[98:101], v[164:167], v[212:215], v[98:101]
	v_mfma_f32_16x16x32_bf16 v[90:93], v[172:175], v[212:215], v[90:93]
	v_mfma_f32_16x16x32_bf16 v[82:85], v[164:167], v[220:223], v[82:85]
	v_mfma_f32_16x16x32_bf16 v[74:77], v[172:175], v[220:223], v[74:77]
	v_mfma_f32_16x16x32_bf16 v[70:73], v[164:167], v[228:231], v[70:73]
	v_mfma_f32_16x16x32_bf16 v[66:69], v[172:175], v[228:231], v[66:69]
	v_mfma_f32_16x16x32_bf16 v[114:117], v[168:171], v[208:211], v[114:117]
	v_mfma_f32_16x16x32_bf16 v[106:109], v[176:179], v[208:211], v[106:109]
	v_mfma_f32_16x16x32_bf16 v[98:101], v[168:171], v[216:219], v[98:101]
	v_mfma_f32_16x16x32_bf16 v[90:93], v[176:179], v[216:219], v[90:93]
	v_mfma_f32_16x16x32_bf16 v[82:85], v[168:171], v[224:227], v[82:85]
	v_mfma_f32_16x16x32_bf16 v[74:77], v[176:179], v[224:227], v[74:77]
	v_mfma_f32_16x16x32_bf16 v[70:73], v[168:171], v[232:235], v[70:73]
	v_mfma_f32_16x16x32_bf16 v[66:69], v[176:179], v[232:235], v[66:69]
	s_setprio 0
	s_barrier
; #define PG8_STAGE(bufoff, gbase, voff) do { _Pragma("unroll") for (int _i = 0; _i < 2; ++_i) \
;         __builtin_amdgcn_global_load_lds((const unsigned*)((const char*)(gbase) + (voff)[_i]), (LAS unsigned*)(lds + (bufoff) + ldsw + _i * 8192), 16, 0, 0); } while (0)
; #define PG8_LDA(dst, b, h) do { _Pragma("unroll") for (int m = 0; m < 4; ++m) _Pragma("unroll") for (int k = 0; k < 2; ++k) dst[m][k] = *(const LAS bf16x8*)(lds + PG8_SA(b, h) + aoff + m * 2048 + k * 1024); } while (0)
; #define PG8_MMA(ai, bj, At, Bt) do { __builtin_amdgcn_s_setprio(1); _Pragma("unroll") for (int m = 0; m < 4; ++m) _Pragma("unroll") for (int n = 0; n < 2; ++n) _Pragma("unroll") for (int k = 0; k < 2; ++k) \
;         acc[ai][bj][m][n] = __builtin_amdgcn_mfma_f32_16x16x32_bf16(Bt[n][k], At[m][k], acc[ai][bj][m][n], 0, 0, 0); __builtin_amdgcn_s_setprio(0); } while (0)
; #define PG8_WAIT_V(n) asm volatile("s_waitcnt vmcnt(" #n ")" ::: "memory")
; #define PG8_WAIT_L(n) asm volatile("s_waitcnt lgkmcnt(" #n ")" ::: "memory")
; #define PG8_BAR __builtin_amdgcn_s_barrier()
; #define PG8_SCHED __builtin_amdgcn_sched_barrier(0)
; template <class Epi, class Sched, bool ALIGN_EPI = false, bool SP2 = false>
; __device__ __forceinline__ void gemm_phase(LAS unsigned char* lds, const Gemm g, const Sched& S, const Epi& E, const int tid) {
;     ...
;         for (int t = 0; t < nt; t += 2) {
;     ...
;             PG8_LDA(At, 1, 1); PG8_STAGE(PG8_SB(1, 0), b3, voffB); PG8_STAGE(PG8_SB(1, 1), b3 + hstep, voffB); PG8_STAGE(PG8_SA(1, 0), a3, voffA);
;             PG8_WAIT_V(8); PG8_WAIT_L(0); PG8_BAR; PG8_MMA(1, 0, At, B0); PG8_MMA(1, 1, At, B1); PG8_BAR; PG8_SCHED;
	s_add_i32 s28, s55, s26
	v_lshl_add_u64 v[140:141], v[140:141], 0, s[36:37]
	s_mov_b32 m0, s28
	ds_read_b128 v[180:183], v145 offset:49152
	ds_read_b128 v[208:211], v145 offset:50176
	ds_read_b128 v[212:215], v145 offset:51200
	ds_read_b128 v[216:219], v145 offset:52224
	ds_read_b128 v[220:223], v145 offset:53248
	ds_read_b128 v[224:227], v145 offset:54272
	ds_read_b128 v[228:231], v145 offset:55296
	ds_read_b128 v[232:235], v145 offset:56320
	global_load_lds_dwordx4 v[140:141], off
	v_lshl_add_u64 v[140:141], v[236:237], 0, s[36:37]
	s_add_i32 m0, s28, 0x2000
	s_add_i32 s28, s57, s26
	global_load_lds_dwordx4 v[140:141], off
	v_lshl_add_u64 v[140:141], v[238:239], 0, s[36:37]
	s_mov_b32 m0, s28
	s_nop 0
	global_load_lds_dwordx4 v[140:141], off
	v_lshl_add_u64 v[140:141], v[240:241], 0, s[36:37]
	s_add_i32 m0, s28, 0x2000
	s_nop 0
	global_load_lds_dwordx4 v[140:141], off
	v_lshl_add_u64 v[140:141], v[242:243], 0, s[36:37]
	s_mov_b32 m0, s41
	s_nop 0
	global_load_lds_dwordx4 v[140:141], off
	v_lshl_add_u64 v[140:141], v[244:245], 0, s[36:37]
	s_mov_b32 m0, s42
	s_nop 0
	global_load_lds_dwordx4 v[140:141], off
	s_waitcnt vmcnt(8)
	s_waitcnt lgkmcnt(0)
	s_barrier
	s_setprio 1
	s_waitcnt lgkmcnt(0)
	v_mfma_f32_16x16x32_bf16 v[62:65], v[146:149], v[180:183], v[62:65]
	v_mfma_f32_16x16x32_bf16 v[58:61], v[154:157], v[180:183], v[58:61]
	v_mfma_f32_16x16x32_bf16 v[54:57], v[146:149], v[212:215], v[54:57]
	v_mfma_f32_16x16x32_bf16 v[46:49], v[154:157], v[212:215], v[46:49]
	v_mfma_f32_16x16x32_bf16 v[38:41], v[146:149], v[220:223], v[38:41]
	v_mfma_f32_16x16x32_bf16 v[30:33], v[154:157], v[220:223], v[30:33]
	v_mfma_f32_16x16x32_bf16 v[22:25], v[146:149], v[228:231], v[22:25]
	v_mfma_f32_16x16x32_bf16 v[14:17], v[154:157], v[228:231], v[14:17]
	v_mfma_f32_16x16x32_bf16 v[62:65], v[150:153], v[208:211], v[62:65]
	v_mfma_f32_16x16x32_bf16 v[58:61], v[160:163], v[208:211], v[58:61]
	v_mfma_f32_16x16x32_bf16 v[54:57], v[150:153], v[216:219], v[54:57]
	v_mfma_f32_16x16x32_bf16 v[46:49], v[160:163], v[216:219], v[46:49]
	v_mfma_f32_16x16x32_bf16 v[38:41], v[150:153], v[224:227], v[38:41]
	v_mfma_f32_16x16x32_bf16 v[30:33], v[160:163], v[224:227], v[30:33]
	v_mfma_f32_16x16x32_bf16 v[22:25], v[150:153], v[232:235], v[22:25]
	v_mfma_f32_16x16x32_bf16 v[14:17], v[160:163], v[232:235], v[14:17]
	s_setprio 0
	s_setprio 1
	v_mfma_f32_16x16x32_bf16 v[50:53], v[164:167], v[180:183], v[50:53]
	v_mfma_f32_16x16x32_bf16 v[42:45], v[172:175], v[180:183], v[42:45]
	v_mfma_f32_16x16x32_bf16 v[34:37], v[164:167], v[212:215], v[34:37]
	v_mfma_f32_16x16x32_bf16 v[26:29], v[172:175], v[212:215], v[26:29]
	v_mfma_f32_16x16x32_bf16 v[18:21], v[164:167], v[220:223], v[18:21]
	v_mfma_f32_16x16x32_bf16 v[10:13], v[172:175], v[220:223], v[10:13]
	v_mfma_f32_16x16x32_bf16 v[6:9], v[164:167], v[228:231], v[6:9]
	v_mfma_f32_16x16x32_bf16 v[2:5], v[172:175], v[228:231], v[2:5]
	v_mfma_f32_16x16x32_bf16 v[50:53], v[168:171], v[208:211], v[50:53]
	v_mfma_f32_16x16x32_bf16 v[42:45], v[176:179], v[208:211], v[42:45]
	v_mfma_f32_16x16x32_bf16 v[34:37], v[168:171], v[216:219], v[34:37]
	v_mfma_f32_16x16x32_bf16 v[26:29], v[176:179], v[216:219], v[26:29]
	v_mfma_f32_16x16x32_bf16 v[18:21], v[168:171], v[224:227], v[18:21]
	v_mfma_f32_16x16x32_bf16 v[10:13], v[176:179], v[224:227], v[10:13]
	v_mfma_f32_16x16x32_bf16 v[6:9], v[168:171], v[232:235], v[6:9]
	v_mfma_f32_16x16x32_bf16 v[2:5], v[176:179], v[232:235], v[2:5]
	s_setprio 0
	s_barrier
	s_add_u32 s52, s52, 0x100
	s_addc_u32 s53, s53, 0
	s_add_u32 s24, s24, 0x100
	s_addc_u32 s25, s25, 0
	s_cmp_ge_i32 s54, s48
	s_mov_b32 s28, s54
	s_cbranch_scc0 .LBB0_531
; __device__ __forceinline__ unsigned cvt_pk_bf16(float lo, float hi) { unsigned r; asm volatile("v_cvt_pk_bf16_f32 %0, %1, %2" : "=v"(r) : "v"(lo), "v"(hi)); return r; }
; #define PG8_WAIT_V(n) asm volatile("s_waitcnt vmcnt(" #n ")" ::: "memory")
; #define PG8_BAR __builtin_amdgcn_s_barrier()
;     __device__ __forceinline__ void operator()(const f32x4 (&acc)[2][2][4][2], const Unit& u, int wr, int wc, int fr, int fq) const {
;         const int row0 = u.pm * BM + wr * 64 + fr + (u.part > 0 ? u.part * T_CTX : 0), col0 = u.pn * BM + wc * 32 + 8 * fq;
; #pragma unroll
;         for (int ai = 0; ai < 2; ++ai)
; #pragma unroll
;             for (int m = 0; m < 4; ++m) {
;                 bf16_t* p = Z + (size_t)(row0 + ai * HALF + m * 16) * DM + col0;
; #pragma unroll
;                 for (int bj = 0; bj < 2; ++bj) { const f32x4 v0 = acc[ai][bj][m][0], v1 = acc[ai][bj][m][1];
;                     *(u32x4*)(p + bj * HALF) = (u32x4){cvt_pk_bf16(v0[0], v0[1]), cvt_pk_bf16(v0[2], v0[3]), cvt_pk_bf16(v1[0], v1[1]), cvt_pk_bf16(v1[2], v1[3])}; }
;             }
;     }
; template <class Epi, class Sched, bool ALIGN_EPI = false, bool SP2 = false>
; __device__ __forceinline__ void gemm_phase(LAS unsigned char* lds, const Gemm g, const Sched& S, const Epi& E, const int tid) {
;     ...
;         if constexpr (!Epi::AFTER_DRAIN) { E(acc, cur, wr, wc, fr, fq); S.done(cur); }
;         if (!has_next) break;
; #pragma unroll
;         for (int a = 0; a < 2; ++a)
; #pragma unroll
;             for (int b = 0; b < 2; ++b)
; #pragma unroll
;                 for (int m = 0; m < 4; ++m)
; #pragma unroll
;                     for (int n = 0; n < 2; ++n) acc[a][b][m][n] = (f32x4){0.f, 0.f, 0.f, 0.f};
;         cur = nxt; cA = nA; cB = nB; ++ui;
;         if constexpr (ALIGN_EPI) { if (wr == 1) PG8_BAR; }
;     }
;     PG8_WAIT_V(0);
	s_max_i32 s24, s49, 0
	s_lshl_b32 s21, s51, 8
	s_lshl_b32 s24, s24, 11
	s_add_i32 s21, s21, s24
	v_add_u32_e32 v146, s21, v142
	v_lshl_or_b32 v140, s50, 8, v144
	v_ashrrev_i32_e32 v147, 31, v146
	v_ashrrev_i32_e32 v141, 31, v140
	v_lshlrev_b64 v[148:149], 11, v[146:147]
	v_lshl_add_u64 v[148:149], s[12:13], 0, v[148:149]
	v_lshlrev_b64 v[150:151], 1, v[140:141]
	v_lshl_add_u64 v[140:141], v[148:149], 0, v[150:151]
	v_cvt_pk_bf16_f32 v126, v126, v127
	v_cvt_pk_bf16_f32 v127, v128, v129
	v_cvt_pk_bf16_f32 v128, v122, v123
	v_cvt_pk_bf16_f32 v129, v124, v125
	global_store_dwordx4 v[140:141], v[126:129], off
	v_cvt_pk_bf16_f32 v114, v114, v115
	v_cvt_pk_bf16_f32 v115, v116, v117
	v_cvt_pk_bf16_f32 v116, v106, v107
	v_or_b32_e32 v106, 16, v146
	v_ashrrev_i32_e32 v107, 31, v106
	v_lshlrev_b64 v[106:107], 11, v[106:107]
	v_lshl_add_u64 v[106:107], s[12:13], 0, v[106:107]
	v_cvt_pk_bf16_f32 v117, v108, v109
	global_store_dwordx4 v[140:141], v[114:117], off offset:256
	s_mov_b32 s21, 0x40000
	s_mov_b64 s[24:25], 0x40000
	v_lshl_add_u64 v[114:115], v[106:107], 0, v[150:151]
	v_cvt_pk_bf16_f32 v106, v118, v119
	v_cvt_pk_bf16_f32 v107, v120, v121
	v_cvt_pk_bf16_f32 v108, v110, v111
	v_cvt_pk_bf16_f32 v109, v112, v113
	global_store_dwordx4 v[114:115], v[106:109], off
	v_cvt_pk_bf16_f32 v98, v98, v99
	v_cvt_pk_bf16_f32 v99, v100, v101
	v_cvt_pk_bf16_f32 v100, v90, v91
	v_or_b32_e32 v90, 32, v146
	v_ashrrev_i32_e32 v91, 31, v90
	v_lshlrev_b64 v[90:91], 11, v[90:91]
	v_lshl_add_u64 v[90:91], s[12:13], 0, v[90:91]
	v_cvt_pk_bf16_f32 v101, v92, v93
	global_store_dwordx4 v[114:115], v[98:101], off offset:256
	s_mov_b32 s49, s44
	s_mov_b32 s48, s46
	v_lshl_add_u64 v[98:99], v[90:91], 0, v[150:151]
	v_cvt_pk_bf16_f32 v90, v102, v103
	v_cvt_pk_bf16_f32 v91, v104, v105
	v_cvt_pk_bf16_f32 v92, v94, v95
	v_cvt_pk_bf16_f32 v93, v96, v97
	global_store_dwordx4 v[98:99], v[90:93], off
	v_cvt_pk_bf16_f32 v82, v82, v83
	v_cvt_pk_bf16_f32 v83, v84, v85
	v_cvt_pk_bf16_f32 v84, v74, v75
	v_or_b32_e32 v74, 48, v146
	v_ashrrev_i32_e32 v75, 31, v74
	v_lshlrev_b64 v[74:75], 11, v[74:75]
	v_lshl_add_u64 v[74:75], s[12:13], 0, v[74:75]
	v_cvt_pk_bf16_f32 v85, v76, v77
	global_store_dwordx4 v[98:99], v[82:85], off offset:256
	s_mov_b32 s50, s47
	s_mov_b32 s51, s45
	v_lshl_add_u64 v[82:83], v[74:75], 0, v[150:151]
	v_cvt_pk_bf16_f32 v74, v86, v87
	v_cvt_pk_bf16_f32 v75, v88, v89
	v_cvt_pk_bf16_f32 v76, v78, v79
	v_cvt_pk_bf16_f32 v77, v80, v81
	global_store_dwordx4 v[82:83], v[74:77], off
	v_cvt_pk_bf16_f32 v70, v70, v71
	v_cvt_pk_bf16_f32 v71, v72, v73
	v_cvt_pk_bf16_f32 v72, v66, v67
	v_cvt_pk_bf16_f32 v73, v68, v69
	global_store_dwordx4 v[82:83], v[70:73], off offset:256
	v_cvt_pk_bf16_f32 v62, v62, v63
	v_cvt_pk_bf16_f32 v63, v64, v65
	v_cvt_pk_bf16_f32 v64, v58, v59
	v_add_co_u32_e32 v58, vcc, s21, v140
	v_lshl_add_u64 v[66:67], v[140:141], 0, s[24:25]
	s_nop 0
	v_addc_co_u32_e32 v59, vcc, 0, v141, vcc
	s_mov_b32 s21, 0x48000
	v_cvt_pk_bf16_f32 v65, v60, v61
	global_store_dwordx4 v[58:59], v[62:65], off
	v_cvt_pk_bf16_f32 v50, v50, v51
	v_cvt_pk_bf16_f32 v51, v52, v53
	v_cvt_pk_bf16_f32 v52, v42, v43
	v_cvt_pk_bf16_f32 v53, v44, v45
	global_store_dwordx4 v[66:67], v[50:53], off offset:256
	s_mov_b64 s[24:25], 0x48000
	v_cvt_pk_bf16_f32 v42, v54, v55
	v_cvt_pk_bf16_f32 v43, v56, v57
	v_cvt_pk_bf16_f32 v44, v46, v47
	v_add_co_u32_e32 v46, vcc, s21, v140
	v_lshl_add_u64 v[50:51], v[140:141], 0, s[24:25]
	s_nop 0
	v_addc_co_u32_e32 v47, vcc, 0, v141, vcc
	s_mov_b32 s21, 0x50000
	v_cvt_pk_bf16_f32 v45, v48, v49
	global_store_dwordx4 v[46:47], v[42:45], off
	v_cvt_pk_bf16_f32 v34, v34, v35
	v_cvt_pk_bf16_f32 v35, v36, v37
	v_cvt_pk_bf16_f32 v36, v26, v27
	v_cvt_pk_bf16_f32 v37, v28, v29
	global_store_dwordx4 v[50:51], v[34:37], off offset:256
	s_mov_b64 s[24:25], 0x50000
	v_cvt_pk_bf16_f32 v26, v38, v39
	v_cvt_pk_bf16_f32 v27, v40, v41
	v_cvt_pk_bf16_f32 v28, v30, v31
	v_add_co_u32_e32 v30, vcc, s21, v140
	v_lshl_add_u64 v[34:35], v[140:141], 0, s[24:25]
	s_nop 0
	v_addc_co_u32_e32 v31, vcc, 0, v141, vcc
	s_mov_b32 s21, 0x58000
	v_cvt_pk_bf16_f32 v29, v32, v33
	global_store_dwordx4 v[30:31], v[26:29], off
	v_cvt_pk_bf16_f32 v18, v18, v19
	v_cvt_pk_bf16_f32 v19, v20, v21
	v_cvt_pk_bf16_f32 v20, v10, v11
	v_cvt_pk_bf16_f32 v21, v12, v13
	global_store_dwordx4 v[34:35], v[18:21], off offset:256
	v_cvt_pk_bf16_f32 v10, v22, v23
	v_cvt_pk_bf16_f32 v11, v24, v25
	v_cvt_pk_bf16_f32 v12, v14, v15
	v_add_co_u32_e32 v14, vcc, s21, v140
	s_mov_b64 s[24:25], 0x58000
	s_nop 0
	v_addc_co_u32_e32 v15, vcc, 0, v141, vcc
	v_lshl_add_u64 v[18:19], v[140:141], 0, s[24:25]
	s_and_b64 vcc, exec, s[18:19]
	s_mov_b64 s[24:25], s[0:1]
	s_mov_b64 s[28:29], s[22:23]
	v_cvt_pk_bf16_f32 v13, v16, v17
	global_store_dwordx4 v[14:15], v[10:13], off
	v_cvt_pk_bf16_f32 v6, v6, v7
	v_cvt_pk_bf16_f32 v7, v8, v9
	v_cvt_pk_bf16_f32 v8, v2, v3
	v_cvt_pk_bf16_f32 v9, v4, v5
	global_store_dwordx4 v[18:19], v[6:9], off offset:256
	s_cbranch_vccz .LBB0_517
	s_waitcnt vmcnt(0)
	v_readlane_b32 s60, v254, 41
	v_readlane_b32 s20, v254, 45
	s_cmpk_gt_u32 s14, 0xff
	v_readlane_b32 s61, v254, 42
	v_readlane_b32 s21, v254, 46
	s_cbranch_scc1 .LBB0_535
	s_barrier

; __device__ __forceinline__ unsigned cvt_pk_bf16(float lo, float hi) { unsigned r; asm volatile("v_cvt_pk_bf16_f32 %0, %1, %2" : "=v"(r) : "v"(lo), "v"(hi)); return r; }
; #define SGLU(g_, u_) ((g_) * (u_) * __builtin_amdgcn_rcpf(1.f + __builtin_amdgcn_exp2f(-(g_))))
;     __device__ __forceinline__ void operator()(const f32x4 (&acc)[2][2][4][2], const Unit& u, int wr, int wc, int fr, int fq) const {
;         const int row0 = u.pm * BM + wr * 64 + fr, col0 = u.pn * 128 + wc * 32 + 8 * fq;
; #pragma unroll
;         for (int ai = 0; ai < 2; ++ai)
; #pragma unroll
;             for (int m = 0; m < 4; ++m) {
;                 bf16_t* p = O + (size_t)(row0 + ai * HALF + m * 16) * DFF + col0;
;                 const f32x4 g0 = acc[ai][0][m][0], g1 = acc[ai][0][m][1], u0 = acc[ai][1][m][0], u1 = acc[ai][1][m][1];
;                 u32x4 w;
;     ...
;                 w.x = cvt_pk_bf16(SGLU(g0[0], u0[0]), SGLU(g0[1], u0[1])); w.y = cvt_pk_bf16(SGLU(g0[2], u0[2]), SGLU(g0[3], u0[3]));
;                 w.z = cvt_pk_bf16(SGLU(g1[0], u1[0]), SGLU(g1[1], u1[1])); w.w = cvt_pk_bf16(SGLU(g1[2], u1[2]), SGLU(g1[3], u1[3]));
;     ...
;                 *(u32x4*)p = w;
.LBB0_595:
	v_mul_f32_e32 v122, v122, v126
	v_exp_f32_e64 v126, -v126
	v_mul_f32_e32 v123, v123, v127
	v_mul_f32_e32 v114, v114, v118
	v_exp_f32_e64 v118, -v118
	v_add_f32_e32 v126, 1.0, v126
	v_rcp_f32_e32 v126, v126
	v_mul_f32_e32 v106, v106, v110
	v_add_f32_e32 v118, 1.0, v118
	v_rcp_f32_e32 v118, v118
	v_mul_f32_e32 v122, v122, v126
	v_exp_f32_e64 v126, -v127
	v_exp_f32_e64 v110, -v110
	v_mul_f32_e32 v114, v114, v118
	v_exp_f32_e64 v118, -v119
	v_add_f32_e32 v126, 1.0, v126
	v_rcp_f32_e32 v126, v126
	v_add_f32_e32 v110, 1.0, v110
	v_add_f32_e32 v118, 1.0, v118
	v_rcp_f32_e32 v118, v118
	v_mul_f32_e32 v123, v123, v126
	v_cvt_pk_bf16_f32 v122, v122, v123
	v_mul_f32_e32 v123, v124, v128
	v_exp_f32_e64 v124, -v128
	v_rcp_f32_e32 v110, v110
	v_mul_f32_e32 v115, v115, v119
	v_mul_f32_e32 v115, v115, v118
	v_add_f32_e32 v124, 1.0, v124
	v_rcp_f32_e32 v124, v124
	v_mul_f32_e32 v106, v106, v110
	v_exp_f32_e64 v110, -v111
	v_lshl_or_b32 v142, s19, 7, v148
	v_mul_f32_e32 v123, v123, v124
	v_mul_f32_e32 v124, v125, v129
	v_exp_f32_e64 v125, -v129
	v_add_f32_e32 v110, 1.0, v110
	v_rcp_f32_e32 v110, v110
	v_lshl_add_u32 v150, s18, 8, v146
	v_add_f32_e32 v125, 1.0, v125
	v_rcp_f32_e32 v125, v125
	v_ashrrev_i32_e32 v143, 31, v142
	v_mov_b64_e32 v[140:141], s[8:9]
	v_mad_i64_i32 v[144:145], s[18:19], v150, s56, v[140:141]
	v_mul_f32_e32 v124, v124, v125
	v_cvt_pk_bf16_f32 v123, v123, v124
	v_cvt_pk_bf16_f32 v124, v114, v115
	v_exp_f32_e64 v115, -v120
	v_mul_f32_e32 v114, v116, v120
	v_exp_f32_e64 v116, -v121
	v_lshlrev_b64 v[142:143], 1, v[142:143]
	v_add_f32_e32 v115, 1.0, v115
	v_rcp_f32_e32 v115, v115
	v_add_f32_e32 v116, 1.0, v116
	v_rcp_f32_e32 v116, v116
	v_mul_f32_e32 v107, v107, v111
	v_lshl_add_u64 v[144:145], v[144:145], 0, v[142:143]
	v_mul_f32_e32 v114, v114, v115
	v_mul_f32_e32 v115, v117, v121
	v_mul_f32_e32 v107, v107, v110
	v_mul_f32_e32 v115, v115, v116
	v_cvt_pk_bf16_f32 v125, v114, v115
	global_store_dwordx4 v[144:145], v[122:125], off
	v_cvt_pk_bf16_f32 v106, v106, v107
	v_mul_f32_e32 v107, v108, v112
	v_exp_f32_e64 v108, -v112
	v_mul_f32_e32 v98, v98, v102
	v_exp_f32_e64 v102, -v102
	v_mul_f32_e32 v90, v90, v94
	v_add_f32_e32 v108, 1.0, v108
	v_rcp_f32_e32 v108, v108
	v_add_f32_e32 v102, 1.0, v102
	v_rcp_f32_e32 v102, v102
	v_exp_f32_e64 v94, -v94
	v_mul_f32_e32 v107, v107, v108
	v_mul_f32_e32 v108, v109, v113
	v_exp_f32_e64 v109, -v113
	v_mul_f32_e32 v98, v98, v102
	v_exp_f32_e64 v102, -v103
	v_add_f32_e32 v94, 1.0, v94
	v_add_f32_e32 v109, 1.0, v109
	v_rcp_f32_e32 v109, v109
	v_add_f32_e32 v102, 1.0, v102
	v_rcp_f32_e32 v102, v102
	v_rcp_f32_e32 v94, v94
	v_mul_f32_e32 v99, v99, v103
	v_mul_f32_e32 v108, v108, v109
	v_mul_f32_e32 v99, v99, v102
	v_cvt_pk_bf16_f32 v107, v107, v108
	v_cvt_pk_bf16_f32 v108, v98, v99
	v_exp_f32_e64 v99, -v104
	v_mul_f32_e32 v90, v90, v94
	v_exp_f32_e64 v94, -v95
	v_mul_f32_e32 v98, v100, v104
	v_exp_f32_e64 v100, -v105
	v_add_f32_e32 v99, 1.0, v99
	v_add_f32_e32 v94, 1.0, v94
	v_rcp_f32_e32 v99, v99
	v_add_f32_e32 v100, 1.0, v100
	v_rcp_f32_e32 v94, v94
	v_rcp_f32_e32 v100, v100
	v_or_b32_e32 v114, 16, v150
	v_mad_i64_i32 v[114:115], s[18:19], v114, s56, v[140:141]
	v_mul_f32_e32 v91, v91, v95
	v_lshl_add_u64 v[114:115], v[114:115], 0, v[142:143]
	v_mul_f32_e32 v98, v98, v99
	v_mul_f32_e32 v99, v101, v105
	v_mul_f32_e32 v91, v91, v94
	v_mul_f32_e32 v99, v99, v100
	v_cvt_pk_bf16_f32 v109, v98, v99
	global_store_dwordx4 v[114:115], v[106:109], off
	v_cvt_pk_bf16_f32 v90, v90, v91
	v_mul_f32_e32 v91, v92, v96
	v_exp_f32_e64 v92, -v96
	v_mul_f32_e32 v82, v82, v86
	v_exp_f32_e64 v86, -v86
	v_mul_f32_e32 v74, v74, v78
	v_add_f32_e32 v92, 1.0, v92
	v_rcp_f32_e32 v92, v92
	v_add_f32_e32 v86, 1.0, v86
	v_rcp_f32_e32 v86, v86
	v_exp_f32_e64 v78, -v78
	v_mul_f32_e32 v91, v91, v92
	v_mul_f32_e32 v92, v93, v97
	v_exp_f32_e64 v93, -v97
	v_mul_f32_e32 v82, v82, v86
	v_exp_f32_e64 v86, -v87
	v_add_f32_e32 v78, 1.0, v78
	v_add_f32_e32 v93, 1.0, v93
	v_rcp_f32_e32 v93, v93
	v_add_f32_e32 v86, 1.0, v86
	v_rcp_f32_e32 v86, v86
	v_rcp_f32_e32 v78, v78
	v_mul_f32_e32 v83, v83, v87
	v_mul_f32_e32 v92, v92, v93
	v_mul_f32_e32 v83, v83, v86
	v_cvt_pk_bf16_f32 v91, v91, v92
	v_cvt_pk_bf16_f32 v92, v82, v83
	v_exp_f32_e64 v83, -v88
	v_mul_f32_e32 v74, v74, v78
	v_exp_f32_e64 v78, -v79
	v_mul_f32_e32 v82, v84, v88
	v_exp_f32_e64 v84, -v89
	v_add_f32_e32 v83, 1.0, v83
	v_add_f32_e32 v78, 1.0, v78
	v_rcp_f32_e32 v83, v83
	v_add_f32_e32 v84, 1.0, v84
	v_rcp_f32_e32 v78, v78
	v_rcp_f32_e32 v84, v84
	v_or_b32_e32 v98, 32, v150
	v_mad_i64_i32 v[98:99], s[18:19], v98, s56, v[140:141]
	v_mul_f32_e32 v75, v75, v79
	v_lshl_add_u64 v[98:99], v[98:99], 0, v[142:143]
	v_mul_f32_e32 v82, v82, v83
	v_mul_f32_e32 v83, v85, v89
	v_mul_f32_e32 v75, v75, v78
	v_mul_f32_e32 v83, v83, v84
	v_cvt_pk_bf16_f32 v93, v82, v83
	global_store_dwordx4 v[98:99], v[90:93], off
	v_cvt_pk_bf16_f32 v74, v74, v75
	v_mul_f32_e32 v75, v76, v80
	v_exp_f32_e64 v76, -v80
	v_mul_f32_e32 v66, v66, v70
	v_exp_f32_e64 v70, -v70
	v_mul_f32_e32 v58, v58, v62
	v_add_f32_e32 v76, 1.0, v76
	v_rcp_f32_e32 v76, v76
	v_add_f32_e32 v70, 1.0, v70
	v_rcp_f32_e32 v70, v70
	v_exp_f32_e64 v62, -v62
	v_mul_f32_e32 v75, v75, v76
	v_mul_f32_e32 v76, v77, v81
	v_exp_f32_e64 v77, -v81
	v_mul_f32_e32 v66, v66, v70
	v_exp_f32_e64 v70, -v71
	v_add_f32_e32 v62, 1.0, v62
	v_add_f32_e32 v77, 1.0, v77
	v_rcp_f32_e32 v77, v77
	v_add_f32_e32 v70, 1.0, v70
	v_rcp_f32_e32 v70, v70
	v_rcp_f32_e32 v62, v62
	v_mul_f32_e32 v67, v67, v71
	v_mul_f32_e32 v76, v76, v77
	v_mul_f32_e32 v67, v67, v70
	v_cvt_pk_bf16_f32 v75, v75, v76
	v_cvt_pk_bf16_f32 v76, v66, v67
	v_exp_f32_e64 v67, -v72
	v_mul_f32_e32 v58, v58, v62
; __device__ __forceinline__ unsigned cvt_pk_bf16(float lo, float hi) { unsigned r; asm volatile("v_cvt_pk_bf16_f32 %0, %1, %2" : "=v"(r) : "v"(lo), "v"(hi)); return r; }
; #define SGLU(g_, u_) ((g_) * (u_) * __builtin_amdgcn_rcpf(1.f + __builtin_amdgcn_exp2f(-(g_))))
; #define PG8_BAR __builtin_amdgcn_s_barrier()
;     __device__ __forceinline__ void operator()(const f32x4 (&acc)[2][2][4][2], const Unit& u, int wr, int wc, int fr, int fq) const {
;     ...
;                 bf16_t* p = O + (size_t)(row0 + ai * HALF + m * 16) * DFF + col0;
;                 const f32x4 g0 = acc[ai][0][m][0], g1 = acc[ai][0][m][1], u0 = acc[ai][1][m][0], u1 = acc[ai][1][m][1];
;                 u32x4 w;
;     ...
;                 w.x = cvt_pk_bf16(SGLU(g0[0], u0[0]), SGLU(g0[1], u0[1])); w.y = cvt_pk_bf16(SGLU(g0[2], u0[2]), SGLU(g0[3], u0[3]));
;                 w.z = cvt_pk_bf16(SGLU(g1[0], u1[0]), SGLU(g1[1], u1[1])); w.w = cvt_pk_bf16(SGLU(g1[2], u1[2]), SGLU(g1[3], u1[3]));
;     ...
;                 *(u32x4*)p = w;
; template <class Epi, class Sched, bool ALIGN_EPI = false, bool SP2 = false>
; __device__ __forceinline__ void gemm_phase(LAS unsigned char* lds, const Gemm g, const Sched& S, const Epi& E, const int tid) {
;     ...
;         if (!has_next) break;
; #pragma unroll
;         for (int a = 0; a < 2; ++a)
; #pragma unroll
;             for (int b = 0; b < 2; ++b)
; #pragma unroll
;                 for (int m = 0; m < 4; ++m)
; #pragma unroll
;                     for (int n = 0; n < 2; ++n) acc[a][b][m][n] = (f32x4){0.f, 0.f, 0.f, 0.f};
;         cur = nxt; cA = nA; cB = nB; ++ui;
;         if constexpr (ALIGN_EPI) { if (wr == 1) PG8_BAR; }
	v_exp_f32_e64 v62, -v63
	v_mul_f32_e32 v66, v68, v72
	v_exp_f32_e64 v68, -v73
	v_add_f32_e32 v67, 1.0, v67
	v_add_f32_e32 v62, 1.0, v62
	v_rcp_f32_e32 v67, v67
	v_add_f32_e32 v68, 1.0, v68
	v_rcp_f32_e32 v62, v62
	v_rcp_f32_e32 v68, v68
	v_or_b32_e32 v82, 48, v150
	v_mad_i64_i32 v[82:83], s[18:19], v82, s56, v[140:141]
	v_mul_f32_e32 v59, v59, v63
	v_lshl_add_u64 v[82:83], v[82:83], 0, v[142:143]
	v_mul_f32_e32 v66, v66, v67
	v_mul_f32_e32 v67, v69, v73
	v_mul_f32_e32 v59, v59, v62
	v_mul_f32_e32 v67, v67, v68
	v_cvt_pk_bf16_f32 v77, v66, v67
	global_store_dwordx4 v[82:83], v[74:77], off
	v_cvt_pk_bf16_f32 v58, v58, v59
	v_mul_f32_e32 v59, v60, v64
	v_exp_f32_e64 v60, -v64
	v_mul_f32_e32 v50, v50, v54
	v_exp_f32_e64 v54, -v54
	v_mul_f32_e32 v42, v42, v46
	v_add_f32_e32 v60, 1.0, v60
	v_rcp_f32_e32 v60, v60
	v_add_f32_e32 v54, 1.0, v54
	v_rcp_f32_e32 v54, v54
	v_exp_f32_e64 v46, -v46
	v_mul_f32_e32 v59, v59, v60
	v_mul_f32_e32 v60, v61, v65
	v_exp_f32_e64 v61, -v65
	v_mul_f32_e32 v50, v50, v54
	v_exp_f32_e64 v54, -v55
	v_add_f32_e32 v46, 1.0, v46
	v_add_f32_e32 v61, 1.0, v61
	v_rcp_f32_e32 v61, v61
	v_add_f32_e32 v54, 1.0, v54
	v_rcp_f32_e32 v54, v54
	v_rcp_f32_e32 v46, v46
	v_mul_f32_e32 v51, v51, v55
	v_mul_f32_e32 v60, v60, v61
	v_mul_f32_e32 v51, v51, v54
	v_cvt_pk_bf16_f32 v59, v59, v60
	v_cvt_pk_bf16_f32 v60, v50, v51
	v_exp_f32_e64 v51, -v56
	v_mul_f32_e32 v42, v42, v46
	v_exp_f32_e64 v46, -v47
	v_mul_f32_e32 v50, v52, v56
	v_exp_f32_e64 v52, -v57
	v_add_f32_e32 v51, 1.0, v51
	v_add_f32_e32 v46, 1.0, v46
	v_rcp_f32_e32 v51, v51
	v_add_f32_e32 v52, 1.0, v52
	v_rcp_f32_e32 v46, v46
	v_rcp_f32_e32 v52, v52
	v_add_u32_e32 v66, 0x80, v150
	v_mad_i64_i32 v[66:67], s[18:19], v66, s56, v[140:141]
	v_mul_f32_e32 v43, v43, v47
	v_lshl_add_u64 v[66:67], v[66:67], 0, v[142:143]
	v_mul_f32_e32 v50, v50, v51
	v_mul_f32_e32 v51, v53, v57
	v_mul_f32_e32 v43, v43, v46
	v_mul_f32_e32 v51, v51, v52
	v_cvt_pk_bf16_f32 v61, v50, v51
	global_store_dwordx4 v[66:67], v[58:61], off
	v_cvt_pk_bf16_f32 v42, v42, v43
	v_mul_f32_e32 v43, v44, v48
	v_exp_f32_e64 v44, -v48
	v_mul_f32_e32 v34, v34, v38
	v_exp_f32_e64 v38, -v38
	v_mul_f32_e32 v26, v26, v30
	v_add_f32_e32 v44, 1.0, v44
	v_rcp_f32_e32 v44, v44
	v_add_f32_e32 v38, 1.0, v38
	v_rcp_f32_e32 v38, v38
	v_exp_f32_e64 v30, -v30
	v_mul_f32_e32 v43, v43, v44
	v_mul_f32_e32 v44, v45, v49
	v_exp_f32_e64 v45, -v49
	v_mul_f32_e32 v34, v34, v38
	v_exp_f32_e64 v38, -v39
	v_add_f32_e32 v30, 1.0, v30
	v_add_f32_e32 v45, 1.0, v45
	v_rcp_f32_e32 v45, v45
	v_add_f32_e32 v38, 1.0, v38
	v_rcp_f32_e32 v38, v38
	v_rcp_f32_e32 v30, v30
	v_mul_f32_e32 v35, v35, v39
	v_mul_f32_e32 v44, v44, v45
	v_mul_f32_e32 v35, v35, v38
	v_cvt_pk_bf16_f32 v43, v43, v44
	v_cvt_pk_bf16_f32 v44, v34, v35
	v_exp_f32_e64 v35, -v40
	v_mul_f32_e32 v26, v26, v30
	v_exp_f32_e64 v30, -v31
	v_mul_f32_e32 v34, v36, v40
	v_exp_f32_e64 v36, -v41
	v_add_f32_e32 v35, 1.0, v35
	v_add_f32_e32 v30, 1.0, v30
	v_rcp_f32_e32 v35, v35
	v_add_f32_e32 v36, 1.0, v36
	v_rcp_f32_e32 v30, v30
	v_rcp_f32_e32 v36, v36
	v_add_u32_e32 v50, 0x90, v150
	v_mad_i64_i32 v[50:51], s[18:19], v50, s56, v[140:141]
	v_mul_f32_e32 v27, v27, v31
	v_lshl_add_u64 v[50:51], v[50:51], 0, v[142:143]
	v_mul_f32_e32 v34, v34, v35
	v_mul_f32_e32 v35, v37, v41
	v_mul_f32_e32 v27, v27, v30
	v_mul_f32_e32 v35, v35, v36
	v_cvt_pk_bf16_f32 v45, v34, v35
	global_store_dwordx4 v[50:51], v[42:45], off
	v_cvt_pk_bf16_f32 v26, v26, v27
	v_mul_f32_e32 v27, v28, v32
	v_exp_f32_e64 v28, -v32
	v_mul_f32_e32 v18, v18, v22
	v_exp_f32_e64 v22, -v22
	v_mul_f32_e32 v10, v10, v14
	v_add_f32_e32 v28, 1.0, v28
	v_rcp_f32_e32 v28, v28
	v_add_f32_e32 v22, 1.0, v22
	v_rcp_f32_e32 v22, v22
	v_exp_f32_e64 v14, -v14
	v_mul_f32_e32 v27, v27, v28
	v_mul_f32_e32 v28, v29, v33
	v_exp_f32_e64 v29, -v33
	v_mul_f32_e32 v18, v18, v22
	v_exp_f32_e64 v22, -v23
	v_add_f32_e32 v14, 1.0, v14
	v_add_f32_e32 v29, 1.0, v29
	v_rcp_f32_e32 v29, v29
	v_add_f32_e32 v22, 1.0, v22
	v_rcp_f32_e32 v22, v22
	v_rcp_f32_e32 v14, v14
	v_mul_f32_e32 v19, v19, v23
	v_mul_f32_e32 v28, v28, v29
	v_mul_f32_e32 v19, v19, v22
	v_cvt_pk_bf16_f32 v27, v27, v28
	v_cvt_pk_bf16_f32 v28, v18, v19
	v_exp_f32_e64 v19, -v24
	v_mul_f32_e32 v10, v10, v14
	v_exp_f32_e64 v14, -v15
	v_mul_f32_e32 v18, v20, v24
	v_exp_f32_e64 v20, -v25
	v_add_f32_e32 v19, 1.0, v19
	v_add_f32_e32 v14, 1.0, v14
	v_rcp_f32_e32 v19, v19
	v_add_f32_e32 v20, 1.0, v20
	v_rcp_f32_e32 v14, v14
	v_rcp_f32_e32 v20, v20
	v_add_u32_e32 v34, 0xa0, v150
	v_mad_i64_i32 v[34:35], s[18:19], v34, s56, v[140:141]
	v_mul_f32_e32 v11, v11, v15
	v_lshl_add_u64 v[34:35], v[34:35], 0, v[142:143]
	v_mul_f32_e32 v18, v18, v19
	v_mul_f32_e32 v19, v21, v25
	v_mul_f32_e32 v11, v11, v14
	v_mul_f32_e32 v19, v19, v20
	v_cvt_pk_bf16_f32 v29, v18, v19
	global_store_dwordx4 v[34:35], v[26:29], off
	v_cvt_pk_bf16_f32 v10, v10, v11
	v_mul_f32_e32 v11, v12, v16
	v_exp_f32_e64 v12, -v16
	v_mul_f32_e32 v2, v2, v6
	v_exp_f32_e64 v6, -v6
	v_mul_f32_e32 v3, v3, v7
	v_add_f32_e32 v12, 1.0, v12
	v_rcp_f32_e32 v12, v12
	v_add_f32_e32 v6, 1.0, v6
	v_rcp_f32_e32 v6, v6
	v_add_u32_e32 v18, 0xb0, v150
	v_mul_f32_e32 v11, v11, v12
	v_mul_f32_e32 v12, v13, v17
	v_exp_f32_e64 v13, -v17
	v_mul_f32_e32 v2, v2, v6
	v_exp_f32_e64 v6, -v7
	v_mad_i64_i32 v[18:19], s[18:19], v18, s56, v[140:141]
	v_add_f32_e32 v13, 1.0, v13
	v_add_f32_e32 v6, 1.0, v6
	v_rcp_f32_e32 v13, v13
	v_rcp_f32_e32 v6, v6
	v_lshl_add_u64 v[18:19], v[18:19], 0, v[142:143]
	s_mov_b64 s[18:19], -1
	v_mul_f32_e32 v12, v12, v13
	v_mul_f32_e32 v3, v3, v6
	v_cvt_pk_bf16_f32 v11, v11, v12
	v_cvt_pk_bf16_f32 v12, v2, v3
	v_exp_f32_e64 v3, -v8
	v_mul_f32_e32 v2, v4, v8
	v_exp_f32_e64 v4, -v9
	s_andn2_b64 vcc, exec, s[38:39]
	v_add_f32_e32 v3, 1.0, v3
	v_rcp_f32_e32 v3, v3
	v_add_f32_e32 v4, 1.0, v4
	v_rcp_f32_e32 v4, v4
	v_mul_f32_e32 v2, v2, v3
	v_mul_f32_e32 v3, v5, v9
	v_mul_f32_e32 v3, v3, v4
	v_cvt_pk_bf16_f32 v13, v2, v3
	global_store_dwordx4 v[18:19], v[10:13], off
	s_cbranch_vccnz .LBB0_588
	s_andn2_b64 vcc, exec, s[0:1]
	s_cbranch_vccnz .LBB0_587
	s_barrier
	s_branch .LBB0_587
